# ph5 table conversion loops: v-table row loads issued together with the u-table row loads (two rows in flight per wave), on top of v049
# speedup vs baseline: 1.0002x; 1.0002x over previous
.LBB0_172:
	v_mov_b32_e32 v2, 0xc0
	v_lshl_add_u64 v[26:27], s[8:9], 0, v[20:21]
	v_add_u32_e32 v2, 0, v2
	v_add_u32_e32 v2, 0x20200, v2
	ds_read_b32 v3, v2
	ds_read_b32 v2, v2 offset:4
	s_waitcnt lgkmcnt(0)
	v_readfirstlane_b32 s2, v3
	s_waitcnt lgkmcnt(0)
	v_readfirstlane_b32 s3, v2
	s_add_u32 s2, s8, s2
	s_addc_u32 s3, s9, s3
	v_lshl_add_u64 v[2:3], s[2:3], 0, v[22:23]
	global_load_dwordx4 v[6:9], v[2:3], off offset:48
	global_load_dwordx4 v[10:13], v[2:3], off offset:32
	global_load_dwordx4 v[14:17], v[2:3], off offset:16
	s_nop 0
	global_load_dwordx4 v[2:5], v[2:3], off
	v_mov_b32_e32 v58, 0x202c8
	ds_read_b64 v[58:59], v58
	s_waitcnt lgkmcnt(0)
	v_readfirstlane_b32 s98, v58
	v_readfirstlane_b32 s99, v59
	s_add_u32 s98, s8, s98
	s_addc_u32 s99, s9, s99
	v_lshl_add_u64 v[56:57], s[98:99], 0, v[22:23]
	global_load_dwordx4 v[40:43], v[56:57], off offset:48
	global_load_dwordx4 v[44:47], v[56:57], off offset:32
	global_load_dwordx4 v[48:51], v[56:57], off offset:16
	global_load_dwordx4 v[52:55], v[56:57], off
	s_waitcnt vmcnt(4)
	v_max_f32_e64 v29, |v8|, |v8|
	s_waitcnt vmcnt(1)
	v_max_f32_e64 v28, |v16|, |v16|
	s_waitcnt vmcnt(0)
	v_max_f32_e64 v18, |v5|, |v5|
	v_max_f32_e64 v19, |v4|, |v4|
	v_max_f32_e32 v18, v19, v18
	v_max_f32_e64 v19, |v17|, |v17|
	v_max_f32_e32 v19, v28, v19
	v_max3_f32 v18, |v2|, |v3|, v18
	v_max3_f32 v19, |v14|, |v15|, v19
	v_max3_f32 v18, v18, 0, v19
	v_max_f32_e64 v19, |v13|, |v13|
	v_max_f32_e64 v28, |v12|, |v12|
	v_max_f32_e32 v19, v28, v19
	v_max_f32_e64 v28, |v9|, |v9|
	v_max_f32_e32 v28, v29, v28
	v_max3_f32 v19, |v10|, |v11|, v19
	v_max3_f32 v28, |v6|, |v7|, v28
	v_max3_f32 v18, v18, v19, v28
	s_nop 1
	v_mov_b32_dpp v19, v18 quad_perm:[1,0,3,2] row_mask:0xf bank_mask:0xf bound_ctrl:1
	v_max_f32_e32 v19, v19, v19
	v_max_f32_e32 v18, v18, v19
	s_nop 1
	v_mov_b32_dpp v19, v18 quad_perm:[2,3,0,1] row_mask:0xf bank_mask:0xf bound_ctrl:1
	v_max_f32_e32 v19, v19, v19
	v_max_f32_e32 v18, v18, v19
	s_nop 1
	v_mov_b32_dpp v19, v18 row_half_mirror row_mask:0xf bank_mask:0xf bound_ctrl:1
	v_max_f32_e32 v19, v19, v19
	v_max_f32_e32 v18, v18, v19
	s_nop 1
	v_mov_b32_dpp v19, v18 row_mirror row_mask:0xf bank_mask:0xf bound_ctrl:1
	v_max_f32_e32 v19, v19, v19
	v_max_f32_e32 v18, v18, v19
	s_nop 0
	v_readlane_b32 s13, v18, 32
	v_readlane_b32 s23, v18, 48
	v_readlane_b32 s2, v18, 0
	v_readlane_b32 s3, v18, 16
	v_max_f32_e64 v18, s23, s23
	v_max_f32_e64 v19, s13, s13
	v_max_f32_e32 v18, v19, v18
	v_mov_b32_e32 v19, s3
	v_max3_f32 v18, s2, v19, v18
	s_mov_b32 s13, 0x43e00000
	v_div_scale_f32 v19, s[30:31], v18, v18, s13
	v_rcp_f32_e32 v28, v19
	v_cmp_lt_f32_e64 s[2:3], 0, v18
	v_fma_f32 v29, -v19, v28, 1.0
	v_fmac_f32_e32 v28, v29, v28
	v_div_scale_f32 v29, vcc, s13, v18, s13
	v_mul_f32_e32 v30, v29, v28
	v_fma_f32 v31, -v19, v30, v29
	v_fmac_f32_e32 v30, v31, v28
	v_fma_f32 v19, -v19, v30, v29
	v_div_fmas_f32 v19, v19, v28, v30
	v_div_fixup_f32 v19, v19, v18, s13
	v_cndmask_b32_e64 v19, 0, v19, s[2:3]
	v_mul_f32_e32 v28, v2, v19
	v_mul_f32_e32 v3, v3, v19
	v_mov_b32_e32 v2, v155
	v_cvt_pk_fp8_f32 v2, v28, v3
	v_mul_f32_e32 v3, v4, v19
	v_mul_f32_e32 v4, v5, v19
	v_mul_f32_e32 v5, v15, v19
	v_cvt_pk_fp8_f32 v2, v3, v4 op_sel:[0,0,1]
	v_mul_f32_e32 v4, v14, v19
	v_mov_b32_e32 v3, v155
	v_cvt_pk_fp8_f32 v3, v4, v5
	v_mul_f32_e32 v4, v16, v19
	v_mul_f32_e32 v5, v17, v19
	v_mul_f32_e32 v6, v6, v19
	v_cvt_pk_fp8_f32 v3, v4, v5 op_sel:[0,0,1]
	v_mul_f32_e32 v5, v10, v19
	v_mul_f32_e32 v10, v11, v19
	v_mov_b32_e32 v4, v155
	v_cvt_pk_fp8_f32 v4, v5, v10
	v_mul_f32_e32 v5, v12, v19
	v_mul_f32_e32 v10, v13, v19
	v_mul_f32_e32 v7, v7, v19
	v_cvt_pk_fp8_f32 v4, v5, v10 op_sel:[0,0,1]
	v_mov_b32_e32 v5, v155
	v_cvt_pk_fp8_f32 v5, v6, v7
	v_mul_f32_e32 v6, v8, v19
	v_mul_f32_e32 v7, v9, v19
	v_lshl_add_u64 v[28:29], s[8:9], 0, v[24:25]
	v_cvt_pk_fp8_f32 v5, v6, v7 op_sel:[0,0,1]
	v_add_co_u32_e32 v6, vcc, 0x22000000, v28
	s_nop 1
	v_addc_co_u32_e32 v7, vcc, 0, v29, vcc
	global_store_dwordx4 v[6:7], v[2:5], off
	s_and_saveexec_b64 s[2:3], s[0:1]
	s_cbranch_execz .LBB0_174
	v_add_co_u32_e32 v2, vcc, 0x2a000000, v26
	v_mul_f32_e32 v4, 0x3b124925, v18
	s_nop 0
	v_addc_co_u32_e32 v3, vcc, 0, v27, vcc
	global_store_dword v[2:3], v4, off
.LBB0_174:
	s_or_b64 exec, exec, s[2:3]
	v_mov_b32_e32 v2, 0xc8
	s_nop 0
	v_add_u32_e32 v2, 0, v2
	v_add_u32_e32 v2, 0x20200, v2
	ds_read_b32 v3, v2
	ds_read_b32 v2, v2 offset:4
	s_waitcnt lgkmcnt(1)
	v_readfirstlane_b32 s2, v3
	s_waitcnt lgkmcnt(0)
	v_readfirstlane_b32 s3, v2
	s_add_u32 s2, s8, s2
	s_addc_u32 s3, s9, s3
	v_lshl_add_u64 v[6:7], s[2:3], 0, v[22:23]
	s_waitcnt vmcnt(2)
	v_mov_b32_e32 v2, v40
	v_mov_b32_e32 v3, v41
	v_mov_b32_e32 v4, v42
	v_mov_b32_e32 v5, v43
	v_mov_b32_e32 v8, v44
	v_mov_b32_e32 v9, v45
	v_mov_b32_e32 v10, v46
	v_mov_b32_e32 v11, v47
	v_mov_b32_e32 v12, v48
	v_mov_b32_e32 v13, v49
	v_mov_b32_e32 v14, v50
	v_mov_b32_e32 v15, v51
	v_mov_b32_e32 v16, v52
	v_mov_b32_e32 v17, v53
	v_mov_b32_e32 v18, v54
	v_mov_b32_e32 v19, v55
	v_max_f32_e64 v31, |v4|, |v4|
	v_max_f32_e64 v30, |v14|, |v14|
	v_max_f32_e64 v6, |v19|, |v19|
	v_max_f32_e64 v7, |v18|, |v18|
	v_max_f32_e32 v6, v7, v6
	v_max_f32_e64 v7, |v15|, |v15|
	v_max_f32_e32 v7, v30, v7
	v_max3_f32 v6, |v16|, |v17|, v6
	v_max3_f32 v7, |v12|, |v13|, v7
	v_max3_f32 v6, v6, 0, v7
	v_max_f32_e64 v7, |v11|, |v11|
	v_max_f32_e64 v30, |v10|, |v10|
	v_max_f32_e32 v7, v30, v7
	v_max_f32_e64 v30, |v5|, |v5|
	v_max_f32_e32 v30, v31, v30
	v_max3_f32 v7, |v8|, |v9|, v7
	v_max3_f32 v30, |v2|, |v3|, v30
	v_max3_f32 v6, v6, v7, v30
	s_nop 1
	v_mov_b32_dpp v7, v6 quad_perm:[1,0,3,2] row_mask:0xf bank_mask:0xf bound_ctrl:1
	v_max_f32_e32 v7, v7, v7
	v_max_f32_e32 v6, v6, v7
	s_nop 1
	v_mov_b32_dpp v7, v6 quad_perm:[2,3,0,1] row_mask:0xf bank_mask:0xf bound_ctrl:1
	v_max_f32_e32 v7, v7, v7
	v_max_f32_e32 v6, v6, v7
	s_nop 1
	v_mov_b32_dpp v7, v6 row_half_mirror row_mask:0xf bank_mask:0xf bound_ctrl:1
	v_max_f32_e32 v7, v7, v7
	v_max_f32_e32 v6, v6, v7
	s_nop 1
	v_mov_b32_dpp v7, v6 row_mirror row_mask:0xf bank_mask:0xf bound_ctrl:1
	v_max_f32_e32 v7, v7, v7
	v_max_f32_e32 v6, v6, v7
	s_nop 0
	v_readlane_b32 s13, v6, 32
	v_readlane_b32 s23, v6, 48
	v_readlane_b32 s2, v6, 0
	v_readlane_b32 s3, v6, 16
	v_max_f32_e64 v6, s23, s23
	v_max_f32_e64 v7, s13, s13
	v_max_f32_e32 v6, v7, v6
	v_mov_b32_e32 v7, s3
	v_max3_f32 v30, s2, v7, v6
	s_mov_b32 s13, 0x43e00000
	v_div_scale_f32 v6, s[30:31], v30, v30, s13
	v_rcp_f32_e32 v7, v6
	v_cmp_lt_f32_e64 s[2:3], 0, v30
	v_fma_f32 v31, -v6, v7, 1.0
	v_fmac_f32_e32 v7, v31, v7
	v_div_scale_f32 v31, vcc, s13, v30, s13
	v_mul_f32_e32 v32, v31, v7
	v_fma_f32 v33, -v6, v32, v31
	v_fmac_f32_e32 v32, v33, v7
	v_fma_f32 v6, -v6, v32, v31
	v_div_fmas_f32 v6, v6, v7, v32
	v_div_fixup_f32 v6, v6, v30, s13
	v_cndmask_b32_e64 v31, 0, v6, s[2:3]
	v_mul_f32_e32 v7, v16, v31
	v_mul_f32_e32 v16, v17, v31
	v_mov_b32_e32 v6, v155
	v_cvt_pk_fp8_f32 v6, v7, v16
	v_mul_f32_e32 v7, v18, v31
	v_mul_f32_e32 v16, v19, v31
	v_mul_f32_e32 v12, v12, v31
	v_cvt_pk_fp8_f32 v6, v7, v16 op_sel:[0,0,1]
	v_mul_f32_e32 v13, v13, v31
	v_mov_b32_e32 v7, v155
	v_cvt_pk_fp8_f32 v7, v12, v13
	v_mul_f32_e32 v12, v14, v31
	v_mul_f32_e32 v13, v15, v31
	v_mul_f32_e32 v9, v9, v31
	v_cvt_pk_fp8_f32 v7, v12, v13 op_sel:[0,0,1]
	v_mul_f32_e32 v12, v8, v31
	v_mov_b32_e32 v8, v155
	v_cvt_pk_fp8_f32 v8, v12, v9
	v_mul_f32_e32 v9, v10, v31
	v_mul_f32_e32 v10, v11, v31
	v_mul_f32_e32 v2, v2, v31
	v_cvt_pk_fp8_f32 v8, v9, v10 op_sel:[0,0,1]
	v_mul_f32_e32 v3, v3, v31
	v_mov_b32_e32 v9, v155
	v_cvt_pk_fp8_f32 v9, v2, v3
	v_mul_f32_e32 v2, v4, v31
	v_mul_f32_e32 v3, v5, v31
	v_cvt_pk_fp8_f32 v9, v2, v3 op_sel:[0,0,1]
	v_add_co_u32_e32 v2, vcc, 0x26000000, v28
	s_nop 1
	v_addc_co_u32_e32 v3, vcc, 0, v29, vcc
	global_store_dwordx4 v[2:3], v[6:9], off
	s_and_saveexec_b64 s[2:3], s[0:1]
	s_cbranch_execz .LBB0_171
	v_add_co_u32_e32 v2, vcc, 0x2a000000, v26
	v_mul_f32_e32 v4, 0x3b124925, v30
	s_nop 0
	v_addc_co_u32_e32 v3, vcc, 0, v27, vcc
	global_store_dword v[2:3], v4, off offset:4
	s_branch .LBB0_171

.LBB0_201:
	v_mov_b32_e32 v2, 0xc0
	v_lshl_add_u64 v[26:27], s[4:5], 0, v[20:21]
	v_add_u32_e32 v2, 0, v2
	v_add_u32_e32 v2, 0x20200, v2
	ds_read_b32 v3, v2
	ds_read_b32 v2, v2 offset:4
	s_waitcnt lgkmcnt(0)
	v_readfirstlane_b32 s2, v3
	v_readfirstlane_b32 s3, v2
	s_add_u32 s2, s4, s2
	s_addc_u32 s3, s5, s3
	v_lshl_add_u64 v[2:3], s[2:3], 0, v[22:23]
	global_load_dwordx4 v[6:9], v[2:3], off offset:48
	global_load_dwordx4 v[10:13], v[2:3], off offset:32
	global_load_dwordx4 v[14:17], v[2:3], off offset:16
	s_nop 0
	global_load_dwordx4 v[2:5], v[2:3], off
	v_mov_b32_e32 v58, 0x202c8
	ds_read_b64 v[58:59], v58
	s_waitcnt lgkmcnt(0)
	v_readfirstlane_b32 s98, v58
	v_readfirstlane_b32 s99, v59
	s_add_u32 s98, s4, s98
	s_addc_u32 s99, s5, s99
	v_lshl_add_u64 v[56:57], s[98:99], 0, v[22:23]
	global_load_dwordx4 v[40:43], v[56:57], off offset:48
	global_load_dwordx4 v[44:47], v[56:57], off offset:32
	global_load_dwordx4 v[48:51], v[56:57], off offset:16
	global_load_dwordx4 v[52:55], v[56:57], off
	s_waitcnt vmcnt(4)
	v_max_f32_e64 v29, |v8|, |v8|
	v_max_f32_e64 v28, |v16|, |v16|
	v_max_f32_e64 v18, |v5|, |v5|
	v_max_f32_e64 v19, |v4|, |v4|
	v_max_f32_e32 v18, v19, v18
	v_max_f32_e64 v19, |v17|, |v17|
	v_max_f32_e32 v19, v28, v19
	v_max3_f32 v18, |v2|, |v3|, v18
	v_max3_f32 v19, |v14|, |v15|, v19
	v_max3_f32 v18, v18, 0, v19
	v_max_f32_e64 v19, |v13|, |v13|
	v_max_f32_e64 v28, |v12|, |v12|
	v_max_f32_e32 v19, v28, v19
	v_max_f32_e64 v28, |v9|, |v9|
	v_max_f32_e32 v28, v29, v28
	v_max3_f32 v19, |v10|, |v11|, v19
	v_max3_f32 v28, |v6|, |v7|, v28
	v_max3_f32 v18, v18, v19, v28
	s_nop 1
	v_mov_b32_dpp v19, v18 quad_perm:[1,0,3,2] row_mask:0xf bank_mask:0xf bound_ctrl:1
	v_max_f32_e32 v19, v19, v19
	v_max_f32_e32 v18, v18, v19
	s_nop 1
	v_mov_b32_dpp v19, v18 quad_perm:[2,3,0,1] row_mask:0xf bank_mask:0xf bound_ctrl:1
	v_max_f32_e32 v19, v19, v19
	v_max_f32_e32 v18, v18, v19
	s_nop 1
	v_mov_b32_dpp v19, v18 row_half_mirror row_mask:0xf bank_mask:0xf bound_ctrl:1
	v_max_f32_e32 v19, v19, v19
	v_max_f32_e32 v18, v18, v19
	s_nop 1
	v_mov_b32_dpp v19, v18 row_mirror row_mask:0xf bank_mask:0xf bound_ctrl:1
	v_max_f32_e32 v19, v19, v19
	v_max_f32_e32 v18, v18, v19
	s_nop 0
	v_readlane_b32 s9, v18, 32
	v_readlane_b32 s19, v18, 48
	v_readlane_b32 s2, v18, 0
	v_readlane_b32 s3, v18, 16
	v_max_f32_e64 v18, s19, s19
	v_max_f32_e64 v19, s9, s9
	v_max_f32_e32 v18, v19, v18
	v_mov_b32_e32 v19, s3
	v_max3_f32 v18, s2, v19, v18
	s_mov_b32 s9, 0x43e00000
	v_div_scale_f32 v19, s[20:21], v18, v18, s9
	v_rcp_f32_e32 v28, v19
	v_cmp_lt_f32_e64 s[2:3], 0, v18
	v_fma_f32 v29, -v19, v28, 1.0
	v_fmac_f32_e32 v28, v29, v28
	v_div_scale_f32 v29, vcc, s9, v18, s9
	v_mul_f32_e32 v30, v29, v28
	v_fma_f32 v31, -v19, v30, v29
	v_fmac_f32_e32 v30, v31, v28
	v_fma_f32 v19, -v19, v30, v29
	v_div_fmas_f32 v19, v19, v28, v30
	v_div_fixup_f32 v19, v19, v18, s9
	v_cndmask_b32_e64 v19, 0, v19, s[2:3]
	v_mul_f32_e32 v28, v2, v19
	v_mul_f32_e32 v3, v3, v19
	v_mov_b32_e32 v2, v155
	v_cvt_pk_fp8_f32 v2, v28, v3
	v_mul_f32_e32 v3, v4, v19
	v_mul_f32_e32 v4, v5, v19
	v_mul_f32_e32 v5, v15, v19
	v_cvt_pk_fp8_f32 v2, v3, v4 op_sel:[0,0,1]
	v_mul_f32_e32 v4, v14, v19
	v_mov_b32_e32 v3, v155
	v_cvt_pk_fp8_f32 v3, v4, v5
	v_mul_f32_e32 v4, v16, v19
	v_mul_f32_e32 v5, v17, v19
	v_mul_f32_e32 v6, v6, v19
	v_cvt_pk_fp8_f32 v3, v4, v5 op_sel:[0,0,1]
	v_mul_f32_e32 v5, v10, v19
	v_mul_f32_e32 v10, v11, v19
	v_mov_b32_e32 v4, v155
	v_cvt_pk_fp8_f32 v4, v5, v10
	v_mul_f32_e32 v5, v12, v19
	v_mul_f32_e32 v10, v13, v19
	v_mul_f32_e32 v7, v7, v19
	v_cvt_pk_fp8_f32 v4, v5, v10 op_sel:[0,0,1]
	v_mov_b32_e32 v5, v155
	v_cvt_pk_fp8_f32 v5, v6, v7
	v_mul_f32_e32 v6, v8, v19
	v_mul_f32_e32 v7, v9, v19
	v_lshl_add_u64 v[28:29], s[4:5], 0, v[24:25]
	v_cvt_pk_fp8_f32 v5, v6, v7 op_sel:[0,0,1]
	v_add_co_u32_e32 v6, vcc, 0x22000000, v28
	s_nop 1
	v_addc_co_u32_e32 v7, vcc, 0, v29, vcc
	global_store_dwordx4 v[6:7], v[2:5], off
	s_and_saveexec_b64 s[2:3], s[0:1]
	s_cbranch_execz .LBB0_203
	v_add_co_u32_e32 v2, vcc, 0x2a000000, v26
	v_mul_f32_e32 v4, 0x3b124925, v18
	s_nop 0
	v_addc_co_u32_e32 v3, vcc, 0, v27, vcc
	global_store_dword v[2:3], v4, off
.LBB0_203:
	s_or_b64 exec, exec, s[2:3]
	v_mov_b32_e32 v2, 0xc8
	s_nop 0
	v_add_u32_e32 v2, 0, v2
	v_add_u32_e32 v2, 0x20200, v2
	ds_read_b32 v3, v2
	ds_read_b32 v2, v2 offset:4
	s_waitcnt lgkmcnt(1)
	v_readfirstlane_b32 s2, v3
	s_waitcnt lgkmcnt(0)
	v_readfirstlane_b32 s3, v2
	s_add_u32 s2, s4, s2
	s_addc_u32 s3, s5, s3
	v_lshl_add_u64 v[6:7], s[2:3], 0, v[22:23]
	s_waitcnt vmcnt(2)
	v_mov_b32_e32 v2, v40
	v_mov_b32_e32 v3, v41
	v_mov_b32_e32 v4, v42
	v_mov_b32_e32 v5, v43
	v_mov_b32_e32 v8, v44
	v_mov_b32_e32 v9, v45
	v_mov_b32_e32 v10, v46
	v_mov_b32_e32 v11, v47
	v_mov_b32_e32 v12, v48
	v_mov_b32_e32 v13, v49
	v_mov_b32_e32 v14, v50
	v_mov_b32_e32 v15, v51
	v_mov_b32_e32 v16, v52
	v_mov_b32_e32 v17, v53
	v_mov_b32_e32 v18, v54
	v_mov_b32_e32 v19, v55
	v_max_f32_e64 v31, |v4|, |v4|
	v_max_f32_e64 v30, |v14|, |v14|
	v_max_f32_e64 v6, |v19|, |v19|
	v_max_f32_e64 v7, |v18|, |v18|
	v_max_f32_e32 v6, v7, v6
	v_max_f32_e64 v7, |v15|, |v15|
	v_max_f32_e32 v7, v30, v7
	v_max3_f32 v6, |v16|, |v17|, v6
	v_max3_f32 v7, |v12|, |v13|, v7
	v_max3_f32 v6, v6, 0, v7
	v_max_f32_e64 v7, |v11|, |v11|
	v_max_f32_e64 v30, |v10|, |v10|
	v_max_f32_e32 v7, v30, v7
	v_max_f32_e64 v30, |v5|, |v5|
	v_max_f32_e32 v30, v31, v30
	v_max3_f32 v7, |v8|, |v9|, v7
	v_max3_f32 v30, |v2|, |v3|, v30
	v_max3_f32 v6, v6, v7, v30
	s_nop 1
	v_mov_b32_dpp v7, v6 quad_perm:[1,0,3,2] row_mask:0xf bank_mask:0xf bound_ctrl:1
	v_max_f32_e32 v7, v7, v7
	v_max_f32_e32 v6, v6, v7
	s_nop 1
	v_mov_b32_dpp v7, v6 quad_perm:[2,3,0,1] row_mask:0xf bank_mask:0xf bound_ctrl:1
	v_max_f32_e32 v7, v7, v7
	v_max_f32_e32 v6, v6, v7
	s_nop 1
	v_mov_b32_dpp v7, v6 row_half_mirror row_mask:0xf bank_mask:0xf bound_ctrl:1
	v_max_f32_e32 v7, v7, v7
	v_max_f32_e32 v6, v6, v7
	s_nop 1
	v_mov_b32_dpp v7, v6 row_mirror row_mask:0xf bank_mask:0xf bound_ctrl:1
	v_max_f32_e32 v7, v7, v7
	v_max_f32_e32 v6, v6, v7
	s_nop 0
	v_readlane_b32 s9, v6, 32
	v_readlane_b32 s19, v6, 48
	v_readlane_b32 s2, v6, 0
	v_readlane_b32 s3, v6, 16
	v_max_f32_e64 v6, s19, s19
	v_max_f32_e64 v7, s9, s9
	v_max_f32_e32 v6, v7, v6
	v_mov_b32_e32 v7, s3
	v_max3_f32 v30, s2, v7, v6
	s_mov_b32 s9, 0x43e00000
	v_div_scale_f32 v6, s[20:21], v30, v30, s9
	v_rcp_f32_e32 v7, v6
	v_cmp_lt_f32_e64 s[2:3], 0, v30
	v_fma_f32 v31, -v6, v7, 1.0
	v_fmac_f32_e32 v7, v31, v7
	v_div_scale_f32 v31, vcc, s9, v30, s9
	v_mul_f32_e32 v32, v31, v7
	v_fma_f32 v33, -v6, v32, v31
	v_fmac_f32_e32 v32, v33, v7
	v_fma_f32 v6, -v6, v32, v31
	v_div_fmas_f32 v6, v6, v7, v32
	v_div_fixup_f32 v6, v6, v30, s9
	v_cndmask_b32_e64 v31, 0, v6, s[2:3]
	v_mul_f32_e32 v7, v16, v31
	v_mul_f32_e32 v16, v17, v31
	v_mov_b32_e32 v6, v155
	v_cvt_pk_fp8_f32 v6, v7, v16
	v_mul_f32_e32 v7, v18, v31
	v_mul_f32_e32 v16, v19, v31
	v_mul_f32_e32 v12, v12, v31
	v_cvt_pk_fp8_f32 v6, v7, v16 op_sel:[0,0,1]
	v_mul_f32_e32 v13, v13, v31
	v_mov_b32_e32 v7, v155
	v_cvt_pk_fp8_f32 v7, v12, v13
	v_mul_f32_e32 v12, v14, v31
	v_mul_f32_e32 v13, v15, v31
	v_mul_f32_e32 v9, v9, v31
	v_cvt_pk_fp8_f32 v7, v12, v13 op_sel:[0,0,1]
	v_mul_f32_e32 v12, v8, v31
	v_mov_b32_e32 v8, v155
	v_cvt_pk_fp8_f32 v8, v12, v9
	v_mul_f32_e32 v9, v10, v31
	v_mul_f32_e32 v10, v11, v31
	v_mul_f32_e32 v2, v2, v31
	v_cvt_pk_fp8_f32 v8, v9, v10 op_sel:[0,0,1]
	v_mul_f32_e32 v3, v3, v31
	v_mov_b32_e32 v9, v155
	v_cvt_pk_fp8_f32 v9, v2, v3
	v_mul_f32_e32 v2, v4, v31
	v_mul_f32_e32 v3, v5, v31
	v_cvt_pk_fp8_f32 v9, v2, v3 op_sel:[0,0,1]
	v_add_co_u32_e32 v2, vcc, 0x26000000, v28
	s_nop 1
	v_addc_co_u32_e32 v3, vcc, 0, v29, vcc
	global_store_dwordx4 v[2:3], v[6:9], off
	s_and_saveexec_b64 s[2:3], s[0:1]
	s_cbranch_execz .LBB0_200
	v_add_co_u32_e32 v2, vcc, 0x2a000000, v26
	v_mul_f32_e32 v4, 0x3b124925, v30
	s_nop 0
	v_addc_co_u32_e32 v3, vcc, 0, v27, vcc
	global_store_dword v[2:3], v4, off offset:4
	s_branch .LBB0_200
